# v67 + code placement: every K-loop MMA segment's first MFMA at address 0 mod 8 (32 s_nop 0 pads in LOAD-segment slack)
# baseline (speedup 1.0000x reference)
.LBB0_297:
	s_add_u32 s47, s38, s46
	s_addc_u32 s66, s39, 0
	s_add_u32 s64, s47, 0x100
	s_addc_u32 s65, s66, 0
	s_and_b64 s[48:49], s[44:45], exec
	s_cselect_b32 s49, s70, s65
	s_cselect_b32 s48, s71, s64
	s_add_u32 s46, s36, s46
	s_addc_u32 s64, s37, 0
	s_add_u32 s46, s46, 0x100
	s_addc_u32 s64, s64, 0
	s_and_b64 s[44:45], s[44:45], exec
	s_cselect_b32 s65, s72, s64
	s_cselect_b32 s64, s73, s46
	s_add_u32 s68, s47, 0x10080
	ds_read_b128 v[150:153], v146
	ds_read_b128 v[154:157], v146 offset:1024
	ds_read_b128 v[158:161], v146 offset:2048
	ds_read_b128 v[162:165], v146 offset:3072
	ds_read_b128 v[166:169], v147
	ds_read_b128 v[170:173], v147 offset:1024
	ds_read_b128 v[174:177], v147 offset:2048
	ds_read_b128 v[178:181], v147 offset:3072
	s_addc_u32 s69, s66, 0
	s_add_i32 s83, s30, s2
	s_add_i32 m0, s16, 0xc000
	s_add_i32 s84, s16, 0xe000
	s_add_i32 s80, s83, 0x2000
	s_add_u32 s66, s64, 0x40000
	s_addc_u32 s67, s65, 0
	s_add_i32 s82, s31, s2
	s_add_i32 s81, s82, 0x2000
	s_add_i32 s79, 0, 0x18000
	s_add_i32 s78, 0, 0x1c000
	s_add_u32 s46, s48, 0x10000
	s_addc_u32 s47, s49, 0
	s_add_i32 s77, s79, s2
	s_add_i32 s75, s77, 0x2000
	s_add_u32 s44, s64, 0x40080
	s_addc_u32 s45, s65, 0
	s_add_i32 s76, s78, s2
	s_add_i32 s74, s76, 0x2000
	v_lshl_add_u64 v[202:203], s[68:69], 0, v[130:131]
	ds_read_b128 v[182:185], v148
	ds_read_b128 v[186:189], v148 offset:1024
	ds_read_b128 v[190:193], v148 offset:2048
	ds_read_b128 v[194:197], v148 offset:3072
	ds_read_b128 v[198:201], v148 offset:4096
	ds_read_b128 v[206:209], v148 offset:5120
	ds_read_b128 v[210:213], v148 offset:6144
	ds_read_b128 v[214:217], v148 offset:7168
	global_load_lds_dwordx4 v[202:203], off
	s_mov_b32 m0, s84
	v_lshl_add_u64 v[202:203], s[68:69], 0, v[132:133]
	global_load_lds_dwordx4 v[202:203], off
	s_waitcnt vmcnt(8) lgkmcnt(0)
	s_setprio 1
	s_barrier
	v_mfma_f32_16x16x32_bf16 v[126:129], v[150:153], v[182:185], v[126:129]
	v_mfma_f32_16x16x32_bf16 v[122:125], v[158:161], v[182:185], v[122:125]
	v_mfma_f32_16x16x32_bf16 v[118:121], v[150:153], v[190:193], v[118:121]
	v_mfma_f32_16x16x32_bf16 v[114:117], v[158:161], v[190:193], v[114:117]
	v_mfma_f32_16x16x32_bf16 v[102:105], v[150:153], v[198:201], v[102:105]
	v_mfma_f32_16x16x32_bf16 v[98:101], v[158:161], v[198:201], v[98:101]
	v_mfma_f32_16x16x32_bf16 v[86:89], v[150:153], v[210:213], v[86:89]
	v_mfma_f32_16x16x32_bf16 v[82:85], v[158:161], v[210:213], v[82:85]
	v_mfma_f32_16x16x32_bf16 v[126:129], v[154:157], v[186:189], v[126:129]
	v_mfma_f32_16x16x32_bf16 v[122:125], v[162:165], v[186:189], v[122:125]
	v_mfma_f32_16x16x32_bf16 v[118:121], v[154:157], v[194:197], v[118:121]
	v_mfma_f32_16x16x32_bf16 v[114:117], v[162:165], v[194:197], v[114:117]
	v_mfma_f32_16x16x32_bf16 v[102:105], v[154:157], v[206:209], v[102:105]
	v_mfma_f32_16x16x32_bf16 v[98:101], v[162:165], v[206:209], v[98:101]
	v_mfma_f32_16x16x32_bf16 v[86:89], v[154:157], v[214:217], v[86:89]
	v_mfma_f32_16x16x32_bf16 v[82:85], v[162:165], v[214:217], v[82:85]
	v_mfma_f32_16x16x32_bf16 v[110:113], v[166:169], v[182:185], v[110:113]
	v_mfma_f32_16x16x32_bf16 v[106:109], v[174:177], v[182:185], v[106:109]
	v_mfma_f32_16x16x32_bf16 v[94:97], v[166:169], v[190:193], v[94:97]
	v_mfma_f32_16x16x32_bf16 v[90:93], v[174:177], v[190:193], v[90:93]
	v_mfma_f32_16x16x32_bf16 v[78:81], v[166:169], v[198:201], v[78:81]
	v_mfma_f32_16x16x32_bf16 v[74:77], v[174:177], v[198:201], v[74:77]
	v_mfma_f32_16x16x32_bf16 v[70:73], v[166:169], v[210:213], v[70:73]
	v_mfma_f32_16x16x32_bf16 v[66:69], v[174:177], v[210:213], v[66:69]
	v_mfma_f32_16x16x32_bf16 v[110:113], v[170:173], v[186:189], v[110:113]
	v_mfma_f32_16x16x32_bf16 v[106:109], v[178:181], v[186:189], v[106:109]
	v_mfma_f32_16x16x32_bf16 v[94:97], v[170:173], v[194:197], v[94:97]
	v_mfma_f32_16x16x32_bf16 v[90:93], v[178:181], v[194:197], v[90:93]
	v_mfma_f32_16x16x32_bf16 v[78:81], v[170:173], v[206:209], v[78:81]
	v_mfma_f32_16x16x32_bf16 v[74:77], v[178:181], v[206:209], v[74:77]
	v_mfma_f32_16x16x32_bf16 v[70:73], v[170:173], v[214:217], v[70:73]
	v_mfma_f32_16x16x32_bf16 v[66:69], v[178:181], v[214:217], v[66:69]
	s_setprio 0
	s_barrier
	s_mov_b32 m0, s83
	v_lshl_add_u64 v[202:203], s[64:65], 0, v[136:137]
	ds_read_b128 v[182:185], v148 offset:16384
	ds_read_b128 v[186:189], v148 offset:17408
	ds_read_b128 v[190:193], v148 offset:18432
	ds_read_b128 v[194:197], v148 offset:19456
	ds_read_b128 v[198:201], v148 offset:20480
	ds_read_b128 v[206:209], v148 offset:21504
	ds_read_b128 v[210:213], v148 offset:22528
	ds_read_b128 v[214:217], v148 offset:23552
	global_load_lds_dwordx4 v[202:203], off
	v_lshl_add_u64 v[218:219], s[64:65], 0, v[134:135]
	s_mov_b32 m0, s80
	v_lshl_add_u64 v[220:221], s[66:67], 0, v[136:137]
	global_load_lds_dwordx4 v[218:219], off
	s_mov_b32 m0, s82
	v_lshl_add_u64 v[222:223], s[48:49], 0, v[132:133]
	global_load_lds_dwordx4 v[220:221], off
	s_mov_b32 m0, s81
	v_lshl_add_u64 v[220:221], s[66:67], 0, v[134:135]
	global_load_lds_dwordx4 v[220:221], off
	s_mov_b32 m0, s16
	v_lshl_add_u64 v[220:221], s[48:49], 0, v[130:131]
	global_load_lds_dwordx4 v[220:221], off
	s_mov_b32 m0, s17
	s_nop 0
	global_load_lds_dwordx4 v[222:223], off
	s_waitcnt vmcnt(8) lgkmcnt(0)
	s_setprio 1
	s_barrier
	v_mfma_f32_16x16x32_bf16 v[62:65], v[150:153], v[182:185], v[62:65]
	v_mfma_f32_16x16x32_bf16 v[58:61], v[158:161], v[182:185], v[58:61]
	v_mfma_f32_16x16x32_bf16 v[54:57], v[150:153], v[190:193], v[54:57]
	v_mfma_f32_16x16x32_bf16 v[50:53], v[158:161], v[190:193], v[50:53]
	v_mfma_f32_16x16x32_bf16 v[38:41], v[150:153], v[198:201], v[38:41]
	v_mfma_f32_16x16x32_bf16 v[34:37], v[158:161], v[198:201], v[34:37]
	v_mfma_f32_16x16x32_bf16 v[22:25], v[150:153], v[210:213], v[22:25]
	v_mfma_f32_16x16x32_bf16 v[18:21], v[158:161], v[210:213], v[18:21]
	v_mfma_f32_16x16x32_bf16 v[62:65], v[154:157], v[186:189], v[62:65]
	v_mfma_f32_16x16x32_bf16 v[58:61], v[162:165], v[186:189], v[58:61]
	v_mfma_f32_16x16x32_bf16 v[54:57], v[154:157], v[194:197], v[54:57]
	v_mfma_f32_16x16x32_bf16 v[50:53], v[162:165], v[194:197], v[50:53]
	v_mfma_f32_16x16x32_bf16 v[38:41], v[154:157], v[206:209], v[38:41]
	v_mfma_f32_16x16x32_bf16 v[34:37], v[162:165], v[206:209], v[34:37]
	v_mfma_f32_16x16x32_bf16 v[22:25], v[154:157], v[214:217], v[22:25]
	v_mfma_f32_16x16x32_bf16 v[18:21], v[162:165], v[214:217], v[18:21]
	v_mfma_f32_16x16x32_bf16 v[46:49], v[166:169], v[182:185], v[46:49]
	v_mfma_f32_16x16x32_bf16 v[42:45], v[174:177], v[182:185], v[42:45]
	v_mfma_f32_16x16x32_bf16 v[30:33], v[166:169], v[190:193], v[30:33]
	v_mfma_f32_16x16x32_bf16 v[26:29], v[174:177], v[190:193], v[26:29]
	v_mfma_f32_16x16x32_bf16 v[14:17], v[166:169], v[198:201], v[14:17]
	v_mfma_f32_16x16x32_bf16 v[10:13], v[174:177], v[198:201], v[10:13]
	v_mfma_f32_16x16x32_bf16 v[6:9], v[166:169], v[210:213], v[6:9]
	v_mfma_f32_16x16x32_bf16 v[2:5], v[174:177], v[210:213], v[2:5]
	v_mfma_f32_16x16x32_bf16 v[46:49], v[170:173], v[186:189], v[46:49]
	v_mfma_f32_16x16x32_bf16 v[42:45], v[178:181], v[186:189], v[42:45]
	v_mfma_f32_16x16x32_bf16 v[30:33], v[170:173], v[194:197], v[30:33]
	v_mfma_f32_16x16x32_bf16 v[26:29], v[178:181], v[194:197], v[26:29]
	v_mfma_f32_16x16x32_bf16 v[14:17], v[170:173], v[206:209], v[14:17]
	v_mfma_f32_16x16x32_bf16 v[10:13], v[178:181], v[206:209], v[10:13]
	v_mfma_f32_16x16x32_bf16 v[6:9], v[170:173], v[214:217], v[6:9]
	v_mfma_f32_16x16x32_bf16 v[2:5], v[178:181], v[214:217], v[2:5]
	s_setprio 0
	s_barrier
	v_add_u32_e32 v149, s79, v145
	ds_read_b128 v[150:153], v149
	ds_read_b128 v[154:157], v149 offset:1024
	ds_read_b128 v[158:161], v149 offset:2048
	ds_read_b128 v[162:165], v149 offset:3072
	v_add_u32_e32 v149, s78, v145
	ds_read_b128 v[166:169], v149
	ds_read_b128 v[170:173], v149 offset:1024
	ds_read_b128 v[174:177], v149 offset:2048
	ds_read_b128 v[178:181], v149 offset:3072
	s_mov_b32 m0, s18
	v_lshl_add_u64 v[224:225], s[46:47], 0, v[130:131]
	ds_read_b128 v[182:185], v148 offset:32768
	ds_read_b128 v[186:189], v148 offset:33792
	ds_read_b128 v[190:193], v148 offset:34816
	ds_read_b128 v[194:197], v148 offset:35840
	ds_read_b128 v[198:201], v148 offset:36864
	ds_read_b128 v[206:209], v148 offset:37888
	ds_read_b128 v[210:213], v148 offset:38912
	ds_read_b128 v[214:217], v148 offset:39936
	global_load_lds_dwordx4 v[224:225], off
	s_mov_b32 m0, s19
	v_lshl_add_u64 v[224:225], s[46:47], 0, v[132:133]
	global_load_lds_dwordx4 v[224:225], off
	s_nop 0
	s_waitcnt vmcnt(8) lgkmcnt(0)
	s_setprio 1
	s_barrier
	v_mfma_f32_16x16x32_bf16 v[126:129], v[150:153], v[182:185], v[126:129]
	v_mfma_f32_16x16x32_bf16 v[122:125], v[158:161], v[182:185], v[122:125]
	v_mfma_f32_16x16x32_bf16 v[118:121], v[150:153], v[190:193], v[118:121]
	v_mfma_f32_16x16x32_bf16 v[114:117], v[158:161], v[190:193], v[114:117]
	v_mfma_f32_16x16x32_bf16 v[102:105], v[150:153], v[198:201], v[102:105]
	v_mfma_f32_16x16x32_bf16 v[98:101], v[158:161], v[198:201], v[98:101]
	v_mfma_f32_16x16x32_bf16 v[86:89], v[150:153], v[210:213], v[86:89]
	v_mfma_f32_16x16x32_bf16 v[82:85], v[158:161], v[210:213], v[82:85]
	v_mfma_f32_16x16x32_bf16 v[126:129], v[154:157], v[186:189], v[126:129]
	v_mfma_f32_16x16x32_bf16 v[122:125], v[162:165], v[186:189], v[122:125]
	v_mfma_f32_16x16x32_bf16 v[118:121], v[154:157], v[194:197], v[118:121]
	v_mfma_f32_16x16x32_bf16 v[114:117], v[162:165], v[194:197], v[114:117]
	v_mfma_f32_16x16x32_bf16 v[102:105], v[154:157], v[206:209], v[102:105]
	v_mfma_f32_16x16x32_bf16 v[98:101], v[162:165], v[206:209], v[98:101]
	v_mfma_f32_16x16x32_bf16 v[86:89], v[154:157], v[214:217], v[86:89]
	v_mfma_f32_16x16x32_bf16 v[82:85], v[162:165], v[214:217], v[82:85]
	v_mfma_f32_16x16x32_bf16 v[110:113], v[166:169], v[182:185], v[110:113]
	v_mfma_f32_16x16x32_bf16 v[106:109], v[174:177], v[182:185], v[106:109]
	v_mfma_f32_16x16x32_bf16 v[94:97], v[166:169], v[190:193], v[94:97]
	v_mfma_f32_16x16x32_bf16 v[90:93], v[174:177], v[190:193], v[90:93]
	v_mfma_f32_16x16x32_bf16 v[78:81], v[166:169], v[198:201], v[78:81]
	v_mfma_f32_16x16x32_bf16 v[74:77], v[174:177], v[198:201], v[74:77]
	v_mfma_f32_16x16x32_bf16 v[70:73], v[166:169], v[210:213], v[70:73]
	v_mfma_f32_16x16x32_bf16 v[66:69], v[174:177], v[210:213], v[66:69]
	v_mfma_f32_16x16x32_bf16 v[110:113], v[170:173], v[186:189], v[110:113]
	v_mfma_f32_16x16x32_bf16 v[106:109], v[178:181], v[186:189], v[106:109]
	v_mfma_f32_16x16x32_bf16 v[94:97], v[170:173], v[194:197], v[94:97]
	v_mfma_f32_16x16x32_bf16 v[90:93], v[178:181], v[194:197], v[90:93]
	v_mfma_f32_16x16x32_bf16 v[78:81], v[170:173], v[206:209], v[78:81]
	v_mfma_f32_16x16x32_bf16 v[74:77], v[178:181], v[206:209], v[74:77]
	v_mfma_f32_16x16x32_bf16 v[70:73], v[170:173], v[214:217], v[70:73]
	v_mfma_f32_16x16x32_bf16 v[66:69], v[178:181], v[214:217], v[66:69]
	s_setprio 0
	s_barrier
	s_mov_b32 m0, s77
	v_lshl_add_u64 v[202:203], v[202:203], 0, s[8:9]
	ds_read_b128 v[182:185], v148 offset:49152
	ds_read_b128 v[186:189], v148 offset:50176
	ds_read_b128 v[190:193], v148 offset:51200
	ds_read_b128 v[194:197], v148 offset:52224
	ds_read_b128 v[198:201], v148 offset:53248
	ds_read_b128 v[206:209], v148 offset:54272
	ds_read_b128 v[210:213], v148 offset:55296
	ds_read_b128 v[214:217], v148 offset:56320
	global_load_lds_dwordx4 v[202:203], off
	s_mov_b32 m0, s75
	v_lshl_add_u64 v[202:203], v[218:219], 0, s[8:9]
	global_load_lds_dwordx4 v[202:203], off
	s_mov_b32 m0, s76
	v_lshl_add_u64 v[202:203], s[44:45], 0, v[136:137]
	global_load_lds_dwordx4 v[202:203], off
	s_mov_b32 m0, s74
	v_lshl_add_u64 v[202:203], s[44:45], 0, v[134:135]
	global_load_lds_dwordx4 v[202:203], off
	s_mov_b32 m0, s28
	v_lshl_add_u64 v[202:203], v[220:221], 0, s[8:9]
	global_load_lds_dwordx4 v[202:203], off
	s_mov_b32 m0, s29
	v_lshl_add_u64 v[202:203], v[222:223], 0, s[8:9]
	global_load_lds_dwordx4 v[202:203], off
	s_nop 0
	s_waitcnt vmcnt(8) lgkmcnt(0)
	s_setprio 1
	s_barrier
	v_mfma_f32_16x16x32_bf16 v[62:65], v[150:153], v[182:185], v[62:65]
	v_mfma_f32_16x16x32_bf16 v[58:61], v[158:161], v[182:185], v[58:61]
	v_mfma_f32_16x16x32_bf16 v[54:57], v[150:153], v[190:193], v[54:57]
	v_mfma_f32_16x16x32_bf16 v[50:53], v[158:161], v[190:193], v[50:53]
	v_mfma_f32_16x16x32_bf16 v[38:41], v[150:153], v[198:201], v[38:41]
	v_mfma_f32_16x16x32_bf16 v[34:37], v[158:161], v[198:201], v[34:37]
	v_mfma_f32_16x16x32_bf16 v[22:25], v[150:153], v[210:213], v[22:25]
	v_mfma_f32_16x16x32_bf16 v[18:21], v[158:161], v[210:213], v[18:21]
	v_mfma_f32_16x16x32_bf16 v[62:65], v[154:157], v[186:189], v[62:65]
	v_mfma_f32_16x16x32_bf16 v[58:61], v[162:165], v[186:189], v[58:61]
	v_mfma_f32_16x16x32_bf16 v[54:57], v[154:157], v[194:197], v[54:57]
	v_mfma_f32_16x16x32_bf16 v[50:53], v[162:165], v[194:197], v[50:53]
	v_mfma_f32_16x16x32_bf16 v[38:41], v[154:157], v[206:209], v[38:41]
	v_mfma_f32_16x16x32_bf16 v[34:37], v[162:165], v[206:209], v[34:37]
	v_mfma_f32_16x16x32_bf16 v[22:25], v[154:157], v[214:217], v[22:25]
	v_mfma_f32_16x16x32_bf16 v[18:21], v[162:165], v[214:217], v[18:21]
	v_mfma_f32_16x16x32_bf16 v[46:49], v[166:169], v[182:185], v[46:49]
	v_mfma_f32_16x16x32_bf16 v[42:45], v[174:177], v[182:185], v[42:45]
	v_mfma_f32_16x16x32_bf16 v[30:33], v[166:169], v[190:193], v[30:33]
	v_mfma_f32_16x16x32_bf16 v[26:29], v[174:177], v[190:193], v[26:29]
	v_mfma_f32_16x16x32_bf16 v[14:17], v[166:169], v[198:201], v[14:17]
	v_mfma_f32_16x16x32_bf16 v[10:13], v[174:177], v[198:201], v[10:13]
	v_mfma_f32_16x16x32_bf16 v[6:9], v[166:169], v[210:213], v[6:9]
	v_mfma_f32_16x16x32_bf16 v[2:5], v[174:177], v[210:213], v[2:5]
	v_mfma_f32_16x16x32_bf16 v[46:49], v[170:173], v[186:189], v[46:49]
	v_mfma_f32_16x16x32_bf16 v[42:45], v[178:181], v[186:189], v[42:45]
	v_mfma_f32_16x16x32_bf16 v[30:33], v[170:173], v[194:197], v[30:33]
	v_mfma_f32_16x16x32_bf16 v[26:29], v[178:181], v[194:197], v[26:29]
	v_mfma_f32_16x16x32_bf16 v[14:17], v[170:173], v[206:209], v[14:17]
	v_mfma_f32_16x16x32_bf16 v[10:13], v[178:181], v[206:209], v[10:13]
	v_mfma_f32_16x16x32_bf16 v[6:9], v[170:173], v[214:217], v[6:9]
	v_mfma_f32_16x16x32_bf16 v[2:5], v[178:181], v[214:217], v[2:5]
	s_setprio 0
	s_barrier
	s_movk_i32 s46, 0x100
	s_andn2_b64 vcc, exec, s[42:43]
	s_mov_b64 s[44:45], -1
	s_mov_b64 s[42:43], 0
	s_cbranch_vccz .LBB0_297
	s_and_b64 vcc, exec, s[10:11]
	s_cbranch_vccz .LBB0_300
	s_barrier
